# P7: workgroups with bit 3 of the block index start each projection GEMM pass 1.6 us later so that the tile epilogue store bursts of the two halves do not coincide
# baseline (speedup 1.0000x reference)
;     __host__ __device__ bool next(int i, Unit& u) const { const long L = (long)i * so.G + so.c; if (L < so.nwg) return so.next(i, u); if (L >= so.nwg + extra) return false; u.pm = so.nM + (int)(L - so.nwg); u.pn = so.nN - 1; return true; }
; #define PG8_WAIT_V(n) asm volatile("s_waitcnt vmcnt(" #n ")" ::: "memory")
; template <class Epi, class Sched, bool ALIGN_EPI = false, bool SP2 = false>
; __device__ __forceinline__ void gemm_phase(PG8_LAS unsigned char* lds, const Gemm g, const Sched& S, const Epi& E) {
;     int tid_o = threadIdx.x; asm volatile("" : "+v"(tid_o)); const int tid = tid_o, wid = __builtin_amdgcn_readfirstlane(tid >> 6), lane = tid & 63, wr = wid >> 2, wc = wid & 3, fr = lane & 15, fq = lane >> 4;
;     const int K = g.K, nt = K / BK;
;     unsigned voffA[2], voffB[2];
; #pragma unroll
;     for (int i = 0; i < 2; ++i) { int R, C; stage_rc(tid * 16 + i * 8192, R, C); const int Rb = Epi::PERM ? ((R & ~31) + perm32(R & 31)) : R;
;         voffA[i] = (unsigned)(R * g.lda + C) * 2u; voffB[i] = (unsigned)(Rb * K + C) * 2u; }
;     const size_t kstep = (size_t)(BK * 2);
;     const size_t hstep = (size_t)HALF * K * 2;
;     const size_t tstep = 2 * hstep; const size_t hstepA = (size_t)HALF * g.lda * 2, tstepA = 2 * hstepA;
;     const unsigned ldsw = (unsigned)wid * 1024u;
;     const int aoff = lds_byte(wr * 64 + fr, fq * 8), boff = lds_byte(wc * 32 + fr, fq * 8);
;     ...
;     Unit cur, nxt; int ui = 0;
;     if (!S.next(0, cur)) return;
;     f32x4 acc[2][2][4][2];
; #pragma unroll
;     for (int a = 0; a < 2; ++a)
; #pragma unroll
;         for (int b = 0; b < 2; ++b)
; #pragma unroll
;             for (int m = 0; m < 4; ++m)
; #pragma unroll
;                 for (int n = 0; n < 2; ++n) acc[a][b][m][n] = (f32x4){0.f, 0.f, 0.f, 0.f};
;     bf16x8 At[4][2], B0[2][2], B1[2][2];
;     const char* cA = (const char*)g.A + (size_t)cur.pm * tstepA; const char* cB = (const char*)g.Bt + (size_t)cur.pn * tstep;
;     S.a_ready(cur);
;     if constexpr (SP2) {
;         PG8_STAGE(PG8_SB(0, 0), cB, voffB); PG8_STAGE(PG8_SB(0, 1), cB + hstep, voffB); PG8_STAGE(PG8_SA(0, 0), cA, voffA); PG8_STAGE(PG8_SA(0, 1), cA + hstepA, voffA);
;         if (wr == 1) PG8_BAR;
;         PG8_WAIT_V(2); PG8_BAR;
;         PG8_STAGE(PG8_SB(1, 0), cB + kstep, voffB); PG8_STAGE(PG8_SA(1, 0), cA + kstep, voffA); PG8_STAGE(PG8_SB(1, 1), cB + hstep + kstep, voffB);
.LBB0_570:
	v_readfirstlane_b32 s8, v164
	v_readfirstlane_b32 s9, v165
	s_mov_b32 s11, s9
	s_mov_b32 s13, s8
	s_mov_b32 s10, s9
	s_mov_b32 s12, s8
	s_mov_b32 s18, s9
	s_mov_b32 s19, s8
	s_mov_b32 s25, s9
	s_mov_b32 s24, s8
	s_waitcnt vmcnt(0)
	v_mov_b32_e32 v14, v162
	s_and_b64 vcc, exec, s[6:7]
	v_readfirstlane_b32 s16, v14
	s_cbranch_vccnz .LBB0_930
	s_bitcmp1_b32 s2, 3
	s_cbranch_scc0 .Lp7_nostagger
	s_sleep 60
.Lp7_nostagger:
	v_lshlrev_b32_e32 v0, 4, v14
	v_add_u32_e32 v1, 0x2000, v0
	v_ashrrev_i32_e32 v2, 31, v1
	v_lshrrev_b32_e32 v2, 22, v2
	v_add_u32_e32 v2, v1, v2
	v_ashrrev_i32_e32 v8, 10, v2
	v_mul_i32_i24_e32 v2, 0x400, v8
	v_sub_u32_e32 v1, v1, v2
	v_lshrrev_b32_e32 v2, 4, v1
	s_lshl_b32 s14, s73, 25
	v_bitop3_b32 v1, v2, v1, 32 bitop3:0x6c
	s_add_u32 s13, s13, s14
	v_ashrrev_i32_e32 v2, 31, v1
	s_addc_u32 s11, s11, 0
	v_lshrrev_b32_e32 v2, 26, v2
	s_add_u32 s36, s13, 0x400000
	v_add_u32_e32 v2, v1, v2
	v_lshlrev_b32_e32 v3, 3, v8
	s_addc_u32 s37, s11, 0
	v_ashrrev_i32_e32 v9, 6, v2
	v_and_b32_e32 v3, -16, v3
	s_add_u32 s38, s12, 0xc400000
	v_add_u32_e32 v3, v9, v3
	s_addc_u32 s39, s10, 0
	v_and_b32_e32 v4, 3, v9
	s_mov_b32 s10, 0xfffe0
	v_lshrrev_b32_e32 v5, 2, v3
	v_lshlrev_b32_e32 v6, 1, v3
	v_and_b32_e32 v2, 0xc0, v2
	v_and_or_b32 v4, v3, s10, v4
	v_and_b32_e32 v5, 4, v5
	v_and_b32_e32 v6, 24, v6
	v_sub_u32_e32 v1, v1, v2
	v_or3_b32 v4, v4, v5, v6
	v_lshlrev_b32_e32 v5, 5, v8
	v_ashrrev_i16_sdwa v1, v167, sext(v1) dst_sel:DWORD dst_unused:UNUSED_PAD src0_sel:DWORD src1_sel:BYTE_0
	v_and_b32_e32 v5, 32, v5
	v_bfe_i32 v10, v1, 0, 16
	v_add_lshl_u32 v1, v5, v10, 1
	v_lshl_add_u32 v138, v4, 12, v1
	v_lshl_add_u32 v140, v3, 12, v1
	v_bfe_i32 v1, v14, 27, 1
	v_lshrrev_b32_e32 v1, 22, v1
	v_add_u32_e32 v1, v0, v1
	v_and_b32_e32 v1, 0xfffffc00, v1
	v_sub_u32_e32 v0, v0, v1
	v_lshrrev_b32_e32 v1, 4, v0
	v_ashrrev_i32_e32 v2, 31, v14
	v_bitop3_b32 v0, v1, v0, 32 bitop3:0x6c
	v_lshrrev_b32_e32 v2, 26, v2
	v_ashrrev_i32_e32 v1, 31, v0
	v_add_u32_e32 v2, v14, v2
	v_lshrrev_b32_e32 v1, 26, v1
	v_ashrrev_i32_e32 v12, 6, v2
	v_add_u32_e32 v1, v0, v1
	v_lshlrev_b32_e32 v2, 3, v12
	v_ashrrev_i32_e32 v11, 6, v1
	v_and_b32_e32 v2, -16, v2
	v_add_u32_e32 v2, v11, v2
	v_and_b32_e32 v3, 3, v11
	v_lshrrev_b32_e32 v4, 2, v2
	v_lshlrev_b32_e32 v5, 1, v2
	v_and_b32_e32 v1, 0xc0, v1
	s_ashr_i32 s20, s16, 6
	v_and_or_b32 v3, v2, s10, v3
	v_and_b32_e32 v4, 4, v4
	v_and_b32_e32 v5, 24, v5
	v_sub_u32_e32 v0, v0, v1
	s_ashr_i32 s17, s16, 8
	s_lshl_b32 s40, s20, 10
	v_or3_b32 v3, v3, v4, v5
	v_lshlrev_b32_e32 v4, 5, v12
	v_ashrrev_i16_sdwa v0, v167, sext(v0) dst_sel:DWORD dst_unused:UNUSED_PAD src0_sel:DWORD src1_sel:BYTE_0
	v_readlane_b32 s10, v236, 13
	v_and_b32_e32 v4, 32, v4
	v_bfe_i32 v13, v0, 0, 16
	v_readlane_b32 s11, v236, 14
	s_add_u32 s12, s38, s10
	v_add_lshl_u32 v0, v4, v13, 1
	s_addc_u32 s13, s39, s11
	s_add_i32 s41, s40, 0
	v_lshl_add_u32 v142, v3, 12, v0
	s_add_i32 m0, s41, 0x10000
	v_lshl_add_u32 v144, v2, 12, v0
	global_load_lds_dwordx4 v142, s[12:13]
	s_add_i32 m0, s41, 0x12000
	s_add_u32 s10, s12, 0x80000
	global_load_lds_dwordx4 v138, s[12:13]
	s_addc_u32 s11, s13, 0
	s_add_i32 m0, s41, 0x14000
	v_mov_b32_e32 v143, v133
	global_load_lds_dwordx4 v142, s[10:11]
	s_add_i32 m0, s41, 0x16000
	v_mov_b32_e32 v139, v133
	global_load_lds_dwordx4 v138, s[10:11]
	v_readlane_b32 s10, v236, 11
	v_readlane_b32 s11, v236, 12
	s_add_u32 s10, s36, s10
	s_addc_u32 s11, s37, s11
	s_add_i32 s58, s41, 0x2000
	s_mov_b32 m0, s41
	s_add_u32 s14, s10, 0x80000
	global_load_lds_dwordx4 v144, s[10:11]
	s_mov_b32 m0, s58
	s_addc_u32 s15, s11, 0
	s_add_i32 s88, s41, 0x4000
	global_load_lds_dwordx4 v140, s[10:11]
	s_mov_b32 m0, s88
	s_add_i32 s89, s41, 0x6000
	global_load_lds_dwordx4 v144, s[14:15]
	s_mov_b32 m0, s89
	v_mov_b32_e32 v145, v133
	global_load_lds_dwordx4 v140, s[14:15]
	v_mov_b32_e32 v141, v133
	s_cmp_eq_u32 s17, 1
	v_lshl_add_u64 v[6:7], s[12:13], 0, v[142:143]
	v_lshl_add_u64 v[4:5], s[12:13], 0, v[138:139]
	v_lshl_add_u64 v[0:1], s[10:11], 0, v[144:145]
	s_cselect_b64 s[14:15], -1, 0
	s_cmp_lg_u32 s17, 1
	v_lshl_add_u64 v[2:3], s[10:11], 0, v[140:141]
	s_cbranch_scc1 .LBB0_573
	s_barrier
